# stagger the 16 dv-slice blocks of each GLA scan by (slice index x 256 cycles) at scan start so they do not request the same K/Q lines simultaneously
# speedup vs baseline: 1.0076x; 1.0002x over previous
; #define GLA_QISSUE(n_, S_) do { if (owave) { int g0i, ci_i, cci; GLA_CHUNK(n_, g0i, ci_i, cci); (void)ci_i; (void)cci; \
;         const bf16_t* qp_ = qsrc + (size_t)(g0i + 16 * oti + jq) * lds_ + h * 256 + 8 * q; \
;         _Pragma("unroll") for (int kk = 0; kk < 8; ++kk) qn[S_][kk] = *(const bf16x8*)(qp_ + 32 * kk); } } while (0)
; __device__ __forceinline__ void gla_scan(const Params& p, LAS unsigned char* lds, int idx, int wv) {
;     ...
;     __syncthreads();
;     GLA_ISSUE(0, 0);
;     GLA_STAGE(0, 0);
;     GLA_ISSUE(1, 1);
;     GLA_ISSUE(2, 0);
;     GLA_QISSUE(0, 0);
;     GLA_QISSUE(1, 1);
;     __syncthreads();
;     for (int n = 0; n < 256; n += 2) { GLA_STEP(n, 0); GLA_STEP(n + 1, 1); }
.LBB0_1855:
	s_and_b64 s[26:27], s[24:25], exec
	s_cselect_b32 s26, s46, 0x28600000
	v_and_b32_e32 v7, 63, v86
	s_add_u32 s26, s94, s26
	s_addc_u32 s27, s95, 0
	s_lshl_b32 s62, s31, 5
	s_lshl_b32 s30, s33, 2
	v_lshlrev_b32_e32 v7, 3, v7
	s_add_u32 s34, s72, s30
	v_and_b32_e32 v7, 24, v7
	s_addc_u32 s35, s73, 0
	v_add_u32_e32 v215, s40, v7
	v_mov_b32_e32 v7, s50
	s_add_i32 s30, 0, 0x17c00
	v_lshl_add_u64 v[188:189], v[84:85], 2, s[34:35]
	v_mad_u32_u24 v85, v5, s44, v7
	v_mov_b32_e32 v7, s30
	s_lshl_b32 s30, s33, 1
	s_add_u32 s28, s28, s30
	s_addc_u32 s29, s29, 0
	v_lshl_add_u64 v[190:191], v[46:47], 1, s[28:29]
	s_lshl_b32 s28, s58, 10
	s_add_u32 s28, s26, s28
	s_addc_u32 s29, s27, 0
	s_lshl_b32 s30, s31, 6
	v_lshlrev_b32_e32 v184, 2, v88
	s_add_u32 s28, s28, s30
	v_add3_u32 v211, s47, v51, v87
	v_lshl_add_u64 v[186:187], v[44:45], 1, s[18:19]
	v_lshlrev_b32_e32 v45, 2, v84
	v_and_b32_e32 v49, 48, v86
	v_lshrrev_b32_e32 v51, 2, v86
	v_or_b32_e32 v84, s90, v184
	v_mad_u32_u24 v86, v5, s44, v7
	s_addc_u32 s29, s29, 0
	v_mov_b32_e32 v7, v4
	v_mul_u32_u24_e32 v44, 0x90, v180
	v_and_or_b32 v51, v51, 3, v48
	v_or_b32_e32 v205, s22, v5
	v_lshl_add_u64 v[192:193], s[28:29], 0, v[6:7]
	s_add_i32 s22, s22, s61
	v_lshlrev_b32_e32 v6, 1, v84
	v_add3_u32 v213, s48, v44, v50
	v_add_u32_e32 v214, s49, v45
	v_lshlrev_b32_e32 v48, 1, v48
	v_mul_lo_u32 v46, v205, s45
	v_mul_u32_u24_e32 v216, 0x90, v5
	v_add3_u32 v218, 0, v44, v50
	v_add_u32_e32 v219, 0, v45
	v_add_u32_e32 v44, s48, v49
	v_or_b32_e32 v221, s22, v5
	v_mad_i32_i24 v45, v51, s44, v181
	v_lshlrev_b32_e32 v5, 2, v84
	v_add_u32_e32 v209, v85, v6
	v_add_u32_e32 v225, v86, v6
	v_mov_b32_e32 v6, v4
	v_add_u32_e32 v212, 0, v49
	v_add_u32_e32 v208, v86, v48
	v_add3_u32 v207, 0, v46, v48
	v_add3_u32 v206, 0, v216, v48
	v_add_u32_e32 v220, v85, v48
	v_add3_u32 v222, s47, v46, v48
	v_add3_u32 v223, s48, v216, v48
	v_mul_i32_i24_e32 v217, 0x210, v51
	v_add_u32_e32 v210, 0, v5
	v_add_u32_e32 v224, s49, v5
	v_mov_b32_e32 v5, v4
	v_add_u32_e32 v229, v44, v216
	v_add_u32_e32 v230, v215, v45
	v_mov_b64_e32 v[106:107], v[6:7]
	v_mov_b64_e32 v[102:103], v[6:7]
	v_mov_b64_e32 v[98:99], v[6:7]
	v_mov_b64_e32 v[94:95], v[6:7]
	v_mov_b64_e32 v[90:91], v[6:7]
	v_mov_b64_e32 v[86:87], v[6:7]
	v_mov_b64_e32 v[50:51], v[6:7]
	v_mov_b64_e32 v[46:47], v[6:7]
	v_add_u32_e32 v226, 64, v224
	v_add_u32_e32 v227, 0x80, v224
	v_add_u32_e32 v228, 0xc0, v224
	s_movk_i32 s63, 0x100
	s_mov_b32 s66, 4
	v_mov_b64_e32 v[104:105], v[4:5]
	v_mov_b64_e32 v[100:101], v[4:5]
	v_mov_b64_e32 v[96:97], v[4:5]
	v_mov_b64_e32 v[92:93], v[4:5]
	v_mov_b64_e32 v[88:89], v[4:5]
	v_mov_b64_e32 v[84:85], v[4:5]
	v_mov_b64_e32 v[48:49], v[4:5]
	v_mov_b64_e32 v[44:45], v[4:5]
	s_waitcnt lgkmcnt(0)
	s_barrier
	s_lshr_b32 s99, s86, 3
	s_and_b32 s99, s99, 15
	s_cmp_eq_u32 s99, 0
	s_cbranch_scc1 .Lgs_stg_done
.Lgs_stg_loop:
	s_sleep 4
	s_sub_i32 s99, s99, 1
	s_cmp_lg_u32 s99, 0
	s_cbranch_scc1 .Lgs_stg_loop
.Lgs_stg_done:
	s_branch .LBB0_1858
.LBB0_1856:
	ds_read_b128 v[156:159], v223
	ds_read_b128 v[160:163], v222
	ds_read_b128 v[164:167], v222 offset:64
	ds_read_b128 v[168:171], v223 offset:64
	s_add_i32 s22, s66, -3
	s_add_i32 s30, s63, -1
	s_waitcnt lgkmcnt(2)
	v_mfma_f32_16x16x32_bf16 v[148:151], v[156:159], v[160:163], v[148:151]
	ds_read_b128 v[156:159], v223 offset:2304
	ds_read_b128 v[172:175], v223 offset:2368
	s_and_b64 s[28:29], s[24:25], exec
	s_cselect_b32 s22, s22, s30
	s_waitcnt lgkmcnt(1)
	v_mfma_f32_16x16x32_bf16 v[152:155], v[156:159], v[160:163], v[152:155]
	v_lshl_add_u32 v6, s22, 6, v221
	v_ashrrev_i32_e32 v7, 31, v6
	v_lshlrev_b64 v[6:7], 12, v[6:7]
	v_mfma_f32_16x16x32_bf16 v[148:151], v[168:171], v[164:167], v[148:151]
	v_lshl_add_u64 v[6:7], v[192:193], 0, v[6:7]
	s_waitcnt lgkmcnt(0)
	v_mfma_f32_16x16x32_bf16 v[152:155], v[172:175], v[164:167], v[152:155]
	s_nop 4
	v_cvt_pk_bf16_f32 v148, v148, v149
	v_cvt_pk_bf16_f32 v149, v150, v151
	global_store_dwordx2 v[6:7], v[148:149], off
	v_cvt_pk_bf16_f32 v148, v152, v153
	v_cvt_pk_bf16_f32 v149, v154, v155
	global_store_dwordx2 v[6:7], v[148:149], off offset:32
